# P7 main loop: static s_setprio 1 for waves 0-3 instead (other half), flips replaced by s_nop
# baseline (speedup 1.0000x reference)
; template <class Epi, class Sched, bool ALIGN_EPI = false, bool SP2 = false>
; __device__ __forceinline__ void gemm_phase(PG8_LAS unsigned char* lds, const Gemm g, const Sched& S, const Epi& E) {
;     ...
;         const bool has_next = S.next(ui + 1, nxt);
;         const char* nA = has_next ? (const char*)g.A + (size_t)nxt.pm * tstep + (size_t)nxt.kt0 * kstep : cA; const char* nB = has_next ? (const char*)g.Bt + (size_t)nxt.pn * tstep + (size_t)nxt.kt0 * kstep : cB;
;         const int nt = cur.nkt;
;         for (int t = 0; t < nt; t += 2) {
;             const bool last = (t == nt - 2);
;             const char* a1 = cA + (size_t)(t + 1) * kstep;
;             const char* a2 = last ? nA : cA + (size_t)(t + 2) * kstep; const char* b2 = last ? nB : cB + (size_t)(t + 2) * kstep;
;     ...
; #pragma unroll
;         for (int a = 0; a < 2; ++a)
; #pragma unroll
;             for (int b = 0; b < 2; ++b)
; #pragma unroll
;                 for (int m = 0; m < 4; ++m)
; #pragma unroll
;                     for (int n = 0; n < 2; ++n) acc[a][b][m][n] = (f32x4){0.f, 0.f, 0.f, 0.f};
.LBB0_1486:
	s_ashr_i32 s21, s20, 31
	s_lshl_b64 s[2:3], s[20:21], 20
	s_add_u32 s42, s6, s2
	s_addc_u32 s43, s7, s3
	s_and_b64 s[2:3], s[40:41], exec
	s_cselect_b32 s21, s43, s49
	s_cselect_b32 s24, s42, s48
	s_ashr_i32 s19, s18, 31
	s_lshl_b64 s[2:3], s[18:19], 20
	s_add_u32 s44, s10, s2
	s_addc_u32 s45, s11, s3
	s_and_b64 s[2:3], s[40:41], exec
	s_cselect_b32 s19, s45, s23
	s_cselect_b32 s25, s44, s22
	s_add_u32 s55, s22, 0x100
	s_addc_u32 s56, s23, 0
	s_add_u32 s48, s48, 0x80080
	v_mov_b32_e32 v2, 0
	s_addc_u32 s49, s49, 0
	s_mov_b32 s57, -2
	v_mov_b32_e32 v3, v2
	v_mov_b32_e32 v4, v2
	v_mov_b32_e32 v5, v2
	v_mov_b32_e32 v10, v2
	v_mov_b32_e32 v11, v2
	v_mov_b32_e32 v12, v2
	v_mov_b32_e32 v13, v2
	v_mov_b32_e32 v18, v2
	v_mov_b32_e32 v19, v2
	v_mov_b32_e32 v20, v2
	v_mov_b32_e32 v21, v2
	v_mov_b32_e32 v26, v2
	v_mov_b32_e32 v27, v2
	v_mov_b32_e32 v28, v2
	v_mov_b32_e32 v29, v2
	s_waitcnt vmcnt(0)
	v_mov_b32_e32 v34, v2
	v_mov_b32_e32 v35, v2
	v_mov_b32_e32 v36, v2
	v_mov_b32_e32 v37, v2
	v_mov_b32_e32 v42, v2
	v_mov_b32_e32 v43, v2
	v_mov_b32_e32 v44, v2
	v_mov_b32_e32 v45, v2
	v_mov_b32_e32 v50, v2
	v_mov_b32_e32 v51, v2
	v_mov_b32_e32 v52, v2
	v_mov_b32_e32 v53, v2
	v_mov_b32_e32 v58, v2
	v_mov_b32_e32 v59, v2
	v_mov_b32_e32 v60, v2
	v_mov_b32_e32 v61, v2
	v_mov_b32_e32 v6, v2
	v_mov_b32_e32 v7, v2
	v_mov_b32_e32 v8, v2
	v_mov_b32_e32 v9, v2
	v_mov_b32_e32 v14, v2
	v_mov_b32_e32 v15, v2
	v_mov_b32_e32 v16, v2
	v_mov_b32_e32 v17, v2
	v_mov_b32_e32 v22, v2
	v_mov_b32_e32 v23, v2
	v_mov_b32_e32 v24, v2
	v_mov_b32_e32 v25, v2
	v_mov_b32_e32 v30, v2
	v_mov_b32_e32 v31, v2
	v_mov_b32_e32 v32, v2
	v_mov_b32_e32 v33, v2
	v_mov_b32_e32 v38, v2
	v_mov_b32_e32 v39, v2
	v_mov_b32_e32 v40, v2
	v_mov_b32_e32 v41, v2
	v_mov_b32_e32 v46, v2
	v_mov_b32_e32 v47, v2
	v_mov_b32_e32 v48, v2
	v_mov_b32_e32 v49, v2
	v_mov_b32_e32 v54, v2
	v_mov_b32_e32 v55, v2
	v_mov_b32_e32 v56, v2
	v_mov_b32_e32 v57, v2
	v_mov_b32_e32 v62, v2
	v_mov_b32_e32 v63, v2
	v_mov_b32_e32 v64, v2
	v_mov_b32_e32 v65, v2
	v_mov_b32_e32 v66, v2
	v_mov_b32_e32 v67, v2
	v_mov_b32_e32 v68, v2
	v_mov_b32_e32 v69, v2
	v_mov_b32_e32 v74, v2
	v_mov_b32_e32 v75, v2
	v_mov_b32_e32 v76, v2
	v_mov_b32_e32 v77, v2
	v_mov_b32_e32 v82, v2
	v_mov_b32_e32 v83, v2
	v_mov_b32_e32 v84, v2
	v_mov_b32_e32 v85, v2
	v_mov_b32_e32 v90, v2
	v_mov_b32_e32 v91, v2
	v_mov_b32_e32 v92, v2
	v_mov_b32_e32 v93, v2
	v_mov_b32_e32 v98, v2
	v_mov_b32_e32 v99, v2
	v_mov_b32_e32 v100, v2
	v_mov_b32_e32 v101, v2
	v_mov_b32_e32 v106, v2
	v_mov_b32_e32 v107, v2
	v_mov_b32_e32 v108, v2
	v_mov_b32_e32 v109, v2
	v_mov_b32_e32 v114, v2
	v_mov_b32_e32 v115, v2
	v_mov_b32_e32 v116, v2
	v_mov_b32_e32 v117, v2
	v_mov_b32_e32 v122, v2
	v_mov_b32_e32 v123, v2
	v_mov_b32_e32 v124, v2
	v_mov_b32_e32 v125, v2
	v_mov_b32_e32 v70, v2
	v_mov_b32_e32 v71, v2
	v_mov_b32_e32 v72, v2
	v_mov_b32_e32 v73, v2
	v_mov_b32_e32 v78, v2
	v_mov_b32_e32 v79, v2
	v_mov_b32_e32 v80, v2
	v_mov_b32_e32 v81, v2
	v_mov_b32_e32 v86, v2
	v_mov_b32_e32 v87, v2
	v_mov_b32_e32 v88, v2
	v_mov_b32_e32 v89, v2
	v_mov_b32_e32 v94, v2
	v_mov_b32_e32 v95, v2
	v_mov_b32_e32 v96, v2
	v_mov_b32_e32 v97, v2
	v_mov_b32_e32 v102, v2
	v_mov_b32_e32 v103, v2
	v_mov_b32_e32 v104, v2
	v_mov_b32_e32 v105, v2
	v_mov_b32_e32 v110, v2
	v_mov_b32_e32 v111, v2
	v_mov_b32_e32 v112, v2
	v_mov_b32_e32 v113, v2
	v_mov_b32_e32 v118, v2
	v_mov_b32_e32 v119, v2
	v_mov_b32_e32 v120, v2
	v_mov_b32_e32 v121, v2
	v_mov_b32_e32 v126, v2
	v_mov_b32_e32 v127, v2
	v_mov_b32_e32 v128, v2
	v_mov_b32_e32 v129, v2
	s_cmp_eq_u32 s16, 0
	s_cbranch_scc1 .Lmy_p7_prio_done
	s_setprio 1
